# speedup vs baseline: 1.0130x; 1.0100x over previous
; __device__ __forceinline__ void phase_dsa_attn(const Params& p, char* smem) {
;     ...
;       for (int kb = wave; kb < nkb; kb += 4) {
;         bf16x8 n0 = b0, n1 = b1;
;         if (kb + 4 < nkb) {
;           const long ktok = tokb + (kb + 4) * 16 + lr;
;           n0 = *(const bf16x8*)(KI + ktok * 64 + g * 8);
;           n1 = *(const bf16x8*)(KI + ktok * 64 + 32 + g * 8);
;         }
; #pragma unroll
;         for (int cb = 0; cb < 4; ++cb) {
;           f32x4 c = (f32x4){0.f, 0.f, 0.f, 0.f};
;           c = __builtin_amdgcn_mfma_f32_16x16x32_bf16(qa[cb][0], b0, c, 0, 0, 0);
;           c = __builtin_amdgcn_mfma_f32_16x16x32_bf16(qa[cb][1], b1, c, 0, 0, 0);
;           float v = fmaxf(c[0], 0.f) * wv[cb][0] + fmaxf(c[1], 0.f) * wv[cb][1] + fmaxf(c[2], 0.f) * wv[cb][2] + fmaxf(c[3], 0.f) * wv[cb][3];
;           v += __shfl_xor(v, 16);
;           if ((g & 1) == 0) {
;             float f = (v + 8.f) * 4096.f;
;             f = fminf(fmaxf(f, 0.f), 65535.f);
;             sscore[(cb * 2 + (g >> 1)) * 4096 + kb * 16 + lr] = (ushort_t)(int)f;
;           }
;         }
;         b0 = n0; b1 = n1;
;       }
.LBB0_337:
	s_or_b64 exec, exec, s[12:13]
	v_mfma_f32_16x16x32_bf16 v[236:239], v[8:11], v[0:3], 0
	v_mfma_f32_16x16x32_bf16 v[240:243], v[20:23], v[0:3], 0
	v_mfma_f32_16x16x32_bf16 v[244:247], v[32:35], v[0:3], 0
	v_mfma_f32_16x16x32_bf16 v[248:251], v[44:47], v[0:3], 0
	v_mfma_f32_16x16x32_bf16 v[236:239], v[12:15], v[4:7], v[236:239]
	v_mfma_f32_16x16x32_bf16 v[240:243], v[24:27], v[4:7], v[240:243]
	v_mfma_f32_16x16x32_bf16 v[244:247], v[36:39], v[4:7], v[244:247]
	v_mfma_f32_16x16x32_bf16 v[248:251], v[48:51], v[4:7], v[248:251]
	s_nop 7
	v_max_f32_e32 v214, 0, v236
	v_max_f32_e32 v215, 0, v237
	v_max_f32_e32 v216, 0, v238
	v_max_f32_e32 v217, 0, v239
	v_mul_f32_e32 v74, v17, v215
	v_fmac_f32_e32 v74, v16, v214
	v_fmac_f32_e32 v74, v18, v216
	v_fmac_f32_e32 v74, v19, v217
	v_max_f32_e32 v214, 0, v240
	v_max_f32_e32 v215, 0, v241
	v_max_f32_e32 v216, 0, v242
	v_max_f32_e32 v217, 0, v243
	v_mul_f32_e32 v75, v29, v215
	v_fmac_f32_e32 v75, v28, v214
	v_fmac_f32_e32 v75, v30, v216
	v_fmac_f32_e32 v75, v31, v217
	v_max_f32_e32 v214, 0, v244
	v_max_f32_e32 v215, 0, v245
	v_max_f32_e32 v216, 0, v246
	v_max_f32_e32 v217, 0, v247
	v_mul_f32_e32 v76, v41, v215
	v_fmac_f32_e32 v76, v40, v214
	v_fmac_f32_e32 v76, v42, v216
	v_fmac_f32_e32 v76, v43, v217
	v_max_f32_e32 v214, 0, v248
	v_max_f32_e32 v215, 0, v249
	v_max_f32_e32 v216, 0, v250
	v_max_f32_e32 v217, 0, v251
	v_mul_f32_e32 v77, v53, v215
	v_fmac_f32_e32 v77, v52, v214
	v_fmac_f32_e32 v77, v54, v216
	v_fmac_f32_e32 v77, v55, v217
	v_mov_b32_e32 v252, v74
	v_mov_b32_e32 v253, v75
	v_mov_b32_e32 v254, v76
	v_mov_b32_e32 v255, v77
	s_nop 1
	v_permlane16_swap_b32_e32 v74, v252
	v_permlane16_swap_b32_e32 v75, v253
	v_permlane16_swap_b32_e32 v76, v254
	v_permlane16_swap_b32_e32 v77, v255
	s_nop 1
	v_add_f32_e32 v74, v74, v252
	v_add_f32_e32 v75, v75, v253
	v_add_f32_e32 v76, v76, v254
	v_add_f32_e32 v77, v77, v255
	v_add_f32_e32 v74, 0x41000000, v74
	v_add_f32_e32 v75, 0x41000000, v75
	v_add_f32_e32 v76, 0x41000000, v76
	v_add_f32_e32 v77, 0x41000000, v77
	v_mul_f32_e32 v74, 0x45800000, v74
	v_mul_f32_e32 v75, 0x45800000, v75
	v_mul_f32_e32 v76, 0x45800000, v76
	v_mul_f32_e32 v77, 0x45800000, v77
	v_max_f32_e32 v74, 0, v74
	v_max_f32_e32 v75, 0, v75
	v_max_f32_e32 v76, 0, v76
	v_max_f32_e32 v77, 0, v77
	v_min_f32_e32 v74, 0x477fff00, v74
	v_min_f32_e32 v75, 0x477fff00, v75
	v_min_f32_e32 v76, 0x477fff00, v76
	v_min_f32_e32 v77, 0x477fff00, v77
	v_cvt_i32_f32_e32 v74, v74
	v_cvt_i32_f32_e32 v75, v75
	v_cvt_i32_f32_e32 v76, v76
	v_cvt_i32_f32_e32 v77, v77
	s_and_saveexec_b64 s[6:7], vcc
	ds_write_b16 v72, v74
	ds_write_b16 v72, v75 offset:16384
	ds_write_b16 v72, v76 offset:32768
	ds_write_b16 v72, v77 offset:49152
	s_branch .LBB0_334

; __device__ __forceinline__ void phase_dsa_attn(const Params& p, char* smem) {
;     ...
;         f32x4 c0 = (f32x4){0.f, 0.f, 0.f, 0.f}, c1 = (f32x4){0.f, 0.f, 0.f, 0.f};
; #pragma unroll
;         for (int ks = 0; ks < 5; ++ks) {
;           const bf16x8 a0 = *(const bf16x8*)(gbuf + lr * 336 + ks * 64 + g * 16);
;           const bf16x8 a1 = *(const bf16x8*)(gbuf + (16 + lr) * 336 + ks * 64 + g * 16);
;           c0 = __builtin_amdgcn_mfma_f32_16x16x32_bf16(a0, qb[ks], c0, 0, 0, 0);
;           c1 = __builtin_amdgcn_mfma_f32_16x16x32_bf16(a1, qb[ks], c1, 0, 0, 0);
;         }
;         float mx = -INFINITY;
; #pragma unroll
;         for (int r = 0; r < 4; ++r) {
;           if (kp * 32 + g * 4 + r >= cnt) c0[r] = -INFINITY;
;           if (kp * 32 + 16 + g * 4 + r >= cnt) c1[r] = -INFINITY;
;           mx = fmaxf(mx, fmaxf(c0[r], c1[r]));
;         }
;         mx = fmaxf(mx, __shfl_xor(mx, 16));
;         mx = fmaxf(mx, __shfl_xor(mx, 32));
;         const float mnew = fmaxf(m_run, mx);
;         const float alpha = __builtin_amdgcn_exp2f(m_run - mnew);
;         m_run = mnew;
;         float ps = 0.f;
; #pragma unroll
;         for (int r = 0; r < 4; ++r) {
;           c0[r] = __builtin_amdgcn_exp2f(c0[r] - mnew);
;           c1[r] = __builtin_amdgcn_exp2f(c1[r] - mnew);
;           ps += c0[r] + c1[r];
;         }
;         l_run = l_run * alpha + ps;
; #pragma unroll
;         for (int cb = 0; cb < 8; ++cb) { o[cb][0] *= alpha; o[cb][1] *= alpha; o[cb][2] *= alpha; o[cb][3] *= alpha; }
;         u32x4 u;
;         u.x = pack2(c0[0], c0[1]); u.y = pack2(c0[2], c0[3]);
;         u.z = pack2(c1[0], c1[1]); u.w = pack2(c1[2], c1[3]);
;         const bf16x8 pf = *(bf16x8*)&u;
; #pragma unroll
;         for (int cb = 0; cb < 8; ++cb) {
;           const int r_ = lr >> 2, c_ = lr & 3;
;           s16x4 v0 = __builtin_amdgcn_ds_read_tr16_b64_v4i16((s16x4 __attribute__((address_space(3)))*)(gbuf + (g * 4 + r_) * 336 + (cb * 16 + c_ * 4) * 2));
;           s16x4 v1 = __builtin_amdgcn_ds_read_tr16_b64_v4i16((s16x4 __attribute__((address_space(3)))*)(gbuf + (16 + g * 4 + r_) * 336 + (cb * 16 + c_ * 4) * 2));
;           bf16x8 a;
;           a[0] = v0[0]; a[1] = v0[1]; a[2] = v0[2]; a[3] = v0[3]; a[4] = v1[0]; a[5] = v1[1]; a[6] = v1[2]; a[7] = v1[3];
;           o[cb] = __builtin_amdgcn_mfma_f32_16x16x32_bf16(a, pf, o[cb], 0, 0, 0);
;         }
.LBB0_385:
	ds_read_b128 v[184:187], v100
	ds_read_b128 v[188:191], v100 offset:64
	ds_read_b128 v[192:195], v100 offset:5376
	ds_read_b128 v[196:199], v100 offset:256
	v_cmp_lt_i32_e64 s[14:15], v182, v170
	s_add_i32 s18, s18, 64
	s_waitcnt lgkmcnt(3)
	v_mfma_f32_16x16x32_bf16 v[184:187], v[184:187], v[12:15], 0
	s_waitcnt lgkmcnt(1)
	v_mfma_f32_16x16x32_bf16 v[192:195], v[192:195], v[12:15], 0
	v_mfma_f32_16x16x32_bf16 v[184:187], v[188:191], v[8:11], v[184:187]
	ds_read_b128 v[188:191], v100 offset:5440
	ds_read_b128 v[200:203], v100 offset:5504
	s_waitcnt lgkmcnt(1)
	v_mfma_f32_16x16x32_bf16 v[188:191], v[188:191], v[8:11], v[192:195]
	s_nop 2
	ds_read_b128 v[192:195], v100 offset:128
	ds_read_b128 v[208:211], v100 offset:192
	s_waitcnt lgkmcnt(1)
	v_mfma_f32_16x16x32_bf16 v[184:187], v[192:195], v[20:23], v[184:187]
	v_mfma_f32_16x16x32_bf16 v[188:191], v[200:203], v[20:23], v[188:191]
	ds_read_b128 v[192:195], v100 offset:5568
	ds_read_b128 v[200:203], v100 offset:5632
	s_waitcnt lgkmcnt(2)
	v_mfma_f32_16x16x32_bf16 v[184:187], v[208:211], v[16:19], v[184:187]
	s_waitcnt lgkmcnt(1)
	v_mfma_f32_16x16x32_bf16 v[188:191], v[192:195], v[16:19], v[188:191]
	v_subrev_u32_e32 v193, 19, v182
	v_mov_b32_e32 v192, s95
	v_cmp_lt_i32_e32 vcc, v193, v170
	v_mfma_f32_16x16x32_bf16 v[184:187], v[196:199], v[24:27], v[184:187]
	v_add_u32_e32 v194, -3, v182
	v_add_u32_e32 v196, -2, v182
	v_cmp_lt_i32_e64 s[6:7], v196, v170
	s_waitcnt lgkmcnt(0)
	v_mfma_f32_16x16x32_bf16 v[188:191], v[200:203], v[24:27], v[188:191]
	s_nop 2
	v_cndmask_b32_e32 v193, v192, v184, vcc
	v_cmp_lt_i32_e32 vcc, v194, v170
	v_max_f32_e32 v195, v193, v193
	s_nop 1
	v_cndmask_b32_e64 v196, v130, v189, s[6:7]
	v_cndmask_b32_e32 v192, v192, v188, vcc
	v_max_f32_e32 v194, v192, v192
	v_max_f32_e32 v194, v195, v194
	v_subrev_u32_e32 v195, 18, v182
	v_cmp_lt_i32_e32 vcc, v195, v170
	v_max_f32_e32 v197, v196, v196
	s_nop 0
	v_cndmask_b32_e32 v195, v130, v185, vcc
	v_max_f32_e32 v198, v195, v195
	v_max_f32_e32 v197, v198, v197
	v_max3_f32 v194, v194, s95, v197
	v_subrev_u32_e32 v197, 17, v182
	v_add_u32_e32 v198, -1, v182
	v_cmp_lt_i32_e64 s[8:9], v197, v170
	v_cmp_lt_i32_e64 s[10:11], v198, v170
	s_nop 0
	v_cndmask_b32_e64 v197, v130, v186, s[8:9]
	v_cndmask_b32_e64 v198, v130, v190, s[10:11]
	v_max_f32_e32 v199, v198, v198
	v_max_f32_e32 v200, v197, v197
	v_max_f32_e32 v199, v200, v199
	v_add_u32_e32 v200, -16, v182
	v_cmp_lt_i32_e64 s[12:13], v200, v170
	v_cndmask_b32_e64 v190, v198, v190, s[14:15]
	v_cndmask_b32_e64 v198, v130, v191, s[14:15]
	v_cndmask_b32_e64 v200, v130, v187, s[12:13]
	v_cndmask_b32_e64 v197, v197, v186, s[12:13]
	v_max_f32_e32 v186, v198, v198
	v_max_f32_e32 v187, v200, v200
	v_max_f32_e32 v186, v187, v186
	v_max3_f32 v186, v194, v199, v186
	v_mov_b32_e32 v187, v186
	s_or_b64 s[8:9], s[12:13], s[8:9]
	s_or_b64 vcc, s[8:9], vcc
	v_cndmask_b32_e32 v191, v193, v184, vcc
	s_or_b64 vcc, s[14:15], s[10:11]
	v_permlane16_swap_b32_e32 v186, v187
	s_nop 1
	v_max_f32_e32 v184, v186, v187
	v_cndmask_b32_e32 v193, v196, v189, vcc
	v_mov_b32_e32 v186, v184
	s_or_b64 vcc, vcc, s[6:7]
	v_cndmask_b32_e32 v188, v192, v188, vcc
	v_cndmask_b32_e64 v185, v195, v185, s[8:9]
	v_permlane32_swap_b32_e32 v184, v186
	s_nop 1
	v_max3_f32 v184, v183, v184, v186
	v_sub_f32_e32 v183, v183, v184
	v_exp_f32_e32 v208, v183
	v_sub_f32_e32 v183, v191, v184
	v_exp_f32_e32 v187, v183
	v_sub_f32_e32 v183, v188, v184
	v_exp_f32_e32 v189, v183
	v_sub_f32_e32 v183, v185, v184
	v_exp_f32_e32 v186, v183
	v_sub_f32_e32 v183, v193, v184
	v_exp_f32_e32 v188, v183
	v_sub_f32_e32 v183, v197, v184
	v_exp_f32_e32 v191, v183
	v_sub_f32_e32 v183, v190, v184
	v_exp_f32_e32 v193, v183
	v_sub_f32_e32 v183, v200, v184
	v_exp_f32_e32 v190, v183
	v_sub_f32_e32 v183, v198, v184
	v_exp_f32_e32 v192, v183
	v_pk_mov_b32 v[194:195], v[186:187], v[186:187] op_sel:[1,0]
	v_pk_mov_b32 v[196:197], v[188:189], v[188:189] op_sel:[1,0]
	v_pk_add_f32 v[210:211], v[186:187], v[188:189]
	v_pk_mov_b32 v[188:189], v[190:191], v[190:191] op_sel:[1,0]
	v_pk_mov_b32 v[198:199], v[192:193], v[192:193] op_sel:[1,0]
	v_pk_add_f32 v[212:213], v[190:191], v[192:193]
	v_cvt_pk_bf16_f32 v186, v194, v195
	v_cvt_pk_bf16_f32 v187, v188, v189
	ds_read_b64_tr_b16 v[192:193], v169 offset:5376
	ds_read_b64_tr_b16 v[190:191], v169
	v_cvt_pk_bf16_f32 v188, v196, v197
	v_cvt_pk_bf16_f32 v189, v198, v199
	ds_read_b64_tr_b16 v[196:197], v169 offset:5408
	ds_read_b64_tr_b16 v[194:195], v169 offset:32
	ds_read_b64_tr_b16 v[198:199], v169 offset:64
	ds_read_b64_tr_b16 v[202:203], v169 offset:96
	ds_read_b64_tr_b16 v[200:201], v169 offset:5440
	ds_read_b64_tr_b16 v[204:205], v169 offset:5472
	v_pk_mul_f32 v[80:81], v[80:81], v[208:209] op_sel_hi:[1,0]
	v_pk_mul_f32 v[82:83], v[82:83], v[208:209] op_sel_hi:[1,0]
	v_pk_mul_f32 v[76:77], v[76:77], v[208:209] op_sel_hi:[1,0]
	v_pk_mul_f32 v[78:79], v[78:79], v[208:209] op_sel_hi:[1,0]
	v_pk_mul_f32 v[40:41], v[40:41], v[208:209] op_sel_hi:[1,0]
	v_pk_mul_f32 v[42:43], v[42:43], v[208:209] op_sel_hi:[1,0]
	v_pk_mul_f32 v[44:45], v[44:45], v[208:209] op_sel_hi:[1,0]
	v_pk_mul_f32 v[46:47], v[46:47], v[208:209] op_sel_hi:[1,0]
	s_waitcnt lgkmcnt(6)
	v_mfma_f32_16x16x32_bf16 v[80:83], v[190:193], v[186:189], v[80:83]
	ds_read_b64_tr_b16 v[190:191], v169 offset:128
	ds_read_b64_tr_b16 v[192:193], v169 offset:5504
	v_pk_mul_f32 v[48:49], v[48:49], v[208:209] op_sel_hi:[1,0]
	v_pk_mul_f32 v[50:51], v[50:51], v[208:209] op_sel_hi:[1,0]
	s_waitcnt lgkmcnt(6)
	v_mfma_f32_16x16x32_bf16 v[76:79], v[194:197], v[186:189], v[76:79]
	v_mul_f32_e64 v32, v32, v208
	v_mul_f32_e64 v33, v33, v208
	v_pk_mul_f32 v[34:35], v[34:35], v[208:209] op_sel_hi:[1,0]
	v_pk_mul_f32 v[28:29], v[28:29], v[208:209] op_sel_hi:[1,0]
	s_waitcnt lgkmcnt(3)
	v_mfma_f32_16x16x32_bf16 v[40:43], v[198:201], v[186:189], v[40:43]
	v_mul_f32_e64 v30, v30, v208
	v_mul_f32_e64 v31, v31, v208
	v_pk_mul_f32 v[36:37], v[36:37], v[208:209] op_sel_hi:[1,0]
	v_pk_mul_f32 v[38:39], v[38:39], v[208:209] op_sel_hi:[1,0]
	s_waitcnt lgkmcnt(2)
	v_mfma_f32_16x16x32_bf16 v[44:47], v[202:205], v[186:189], v[44:47]
	ds_read_b64_tr_b16 v[196:197], v169 offset:5536
	ds_read_b64_tr_b16 v[194:195], v169 offset:160
	ds_read_b64_tr_b16 v[198:199], v169 offset:192
	ds_read_b64_tr_b16 v[202:203], v169 offset:224
	ds_read_b64_tr_b16 v[200:201], v169 offset:5568
	ds_read_b64_tr_b16 v[204:205], v169 offset:5600
	v_add_f32_e32 v183, 0, v211
	v_add_f32_e32 v183, v210, v183
	s_waitcnt lgkmcnt(6)
	v_mfma_f32_16x16x32_bf16 v[48:51], v[190:193], v[186:189], v[48:51]
	v_add_f32_e32 v183, v213, v183
	v_add_f32_e32 v183, v212, v183
	v_fmac_f32_e32 v183, v171, v208
	s_waitcnt lgkmcnt(4)
	v_mfma_f32_16x16x32_bf16 v[32:35], v[194:197], v[186:189], v[32:35]
	s_cmpk_eq_i32 s18, 0x200
	v_add_u32_e32 v182, 32, v182
	s_waitcnt lgkmcnt(1)
	v_mfma_f32_16x16x32_bf16 v[28:31], v[198:201], v[186:189], v[28:31]
	s_waitcnt lgkmcnt(0)
	v_mfma_f32_16x16x32_bf16 v[36:39], v[202:205], v[186:189], v[36:39]
	s_cbranch_scc1 .LBB0_387
; __device__ __forceinline__ void phase_dsa_attn(const Params& p, char* smem) {
;     ...
;         const float mnew = fmaxf(m_run, mx);
;         const float alpha = __builtin_amdgcn_exp2f(m_run - mnew);
;         m_run = mnew;
;         float ps = 0.f;
; #pragma unroll
;         for (int r = 0; r < 4; ++r) {
;           c0[r] = __builtin_amdgcn_exp2f(c0[r] - mnew);
;           c1[r] = __builtin_amdgcn_exp2f(c1[r] - mnew);
;           ps += c0[r] + c1[r];
;         }
;         l_run = l_run * alpha + ps;
	v_mov_b32_e32 v171, v183
	v_mov_b32_e32 v183, v184
	s_branch .LBB0_383
